# speedup vs baseline: 1.0187x; 1.0001x over previous
; __device__ __forceinline__ unsigned pk2(float a, float b) { unsigned r; asm("v_cvt_pk_bf16_f32 %0, %1, %2" : "=v"(r) : "v"(a), "v"(b)); return r; }
; __device__ __forceinline__ void hg_gate(const PRef& P, int slot) {
;     ...
;   for (int row = wv; row < TT; row += nw) {
;     const long off = (long)row * DM + lane * 16;
;     u32x4 a0 = *(const u32x4*)(Of + off), a1 = *(const u32x4*)(Of + off + 8), b0 = *(const u32x4*)(Ob + off), b1 = *(const u32x4*)(Ob + off + 8);
;     u32x4 g0 = *(const u32x4*)(Gg + off), g1 = *(const u32x4*)(Gg + off + 8);
;     float o[16], gg[16]; float ss = 0.f;
; #pragma unroll
;     for (int i = 0; i < 4; ++i) {
;       o[2 * i] = __uint_as_float(a0[i] << 16) + __uint_as_float(b0[i] << 16); o[2 * i + 1] = __uint_as_float(a0[i] & 0xffff0000u) + __uint_as_float(b0[i] & 0xffff0000u);
;       o[8 + 2 * i] = __uint_as_float(a1[i] << 16) + __uint_as_float(b1[i] << 16); o[8 + 2 * i + 1] = __uint_as_float(a1[i] & 0xffff0000u) + __uint_as_float(b1[i] & 0xffff0000u);
;       gg[2 * i] = __uint_as_float(g0[i] << 16); gg[2 * i + 1] = __uint_as_float(g0[i] & 0xffff0000u); gg[8 + 2 * i] = __uint_as_float(g1[i] << 16); gg[8 + 2 * i + 1] = __uint_as_float(g1[i] & 0xffff0000u); }
; #pragma unroll
;     for (int i = 0; i < 16; ++i) ss += o[i] * o[i];
;     ss += __shfl_xor(ss, 1); ss += __shfl_xor(ss, 2); ss += __shfl_xor(ss, 4);
;     const float rs = rsqrtf(ss * (1.f / 128) + 1e-6f);
;     u32x4 w0, w1;
; #pragma unroll
;     for (int i = 0; i < 4; ++i) { w0[i] = pk2(o[2 * i] * rs * gn[2 * i] * gg[2 * i], o[2 * i + 1] * rs * gn[2 * i + 1] * gg[2 * i + 1]);
;       w1[i] = pk2(o[8 + 2 * i] * rs * gn[8 + 2 * i] * gg[8 + 2 * i], o[9 + 2 * i] * rs * gn[9 + 2 * i] * gg[9 + 2 * i]); }
;     *(u32x4*)(Og + off) = w0; *(u32x4*)(Og + off + 8) = w1;
;   }
.LBB0_1061:
	v_add_co_u32_e32 v24, vcc, 0xf4000000, v20
	v_lshl_add_u64 v[28:29], v[20:21], 0, s[16:17]
	s_nop 0
	v_addc_co_u32_e32 v25, vcc, -1, v21, vcc
	global_load_dwordx4 v[24:27], v[24:25], off offset:-16
	s_nop 0
	global_load_dwordx4 v[28:31], v[28:29], off offset:16
	v_add_co_u32_e32 v32, vcc, s15, v20
	v_lshl_add_u64 v[36:37], v[20:21], 0, s[18:19]
	s_nop 0
	v_addc_co_u32_e32 v33, vcc, -1, v21, vcc
	global_load_dwordx4 v[32:35], v[32:33], off offset:-16
	s_nop 0
	global_load_dwordx4 v[36:39], v[36:37], off offset:16
	s_nop 0
	global_load_dwordx4 v[40:43], v[20:21], off
	global_load_dwordx4 v[44:47], v[20:21], off offset:-16
	v_add_u32_e32 v18, s90, v18
	v_lshl_add_u64 v[120:121], v[20:21], 0, s[20:21]
	v_add_co_u32_e32 v122, vcc, 0xf4000000, v120
	s_nop 1
	v_addc_co_u32_e32 v123, vcc, -1, v121, vcc
	v_add_co_u32_e32 v124, vcc, 0xf8000000, v120
	s_nop 1
	v_addc_co_u32_e32 v125, vcc, -1, v121, vcc
	global_load_dword v126, v[120:121], off
	global_load_dword v127, v[122:123], off
	global_load_dword v128, v[124:125], off
	s_waitcnt vmcnt(3)
	v_lshlrev_b32_e32 v19, 16, v24
	v_and_b32_e32 v24, 0xffff0000, v24
	v_lshlrev_b32_e32 v51, 16, v28
	v_and_b32_e32 v50, 0xffff0000, v28
	v_lshlrev_b32_e32 v48, 16, v32
	v_and_b32_e32 v32, 0xffff0000, v32
	v_add_f32_e32 v52, v32, v24
	v_lshlrev_b32_e32 v24, 16, v25
	v_lshlrev_b32_e32 v28, 16, v33
	v_add_f32_e32 v55, v28, v24
	v_and_b32_e32 v24, 0xffff0000, v33
	v_lshlrev_b32_e32 v33, 16, v29
	v_and_b32_e32 v32, 0xffff0000, v29
	v_lshlrev_b32_e32 v28, 16, v26
	v_lshlrev_b32_e32 v29, 16, v34
	v_and_b32_e32 v25, 0xffff0000, v25
	v_add_f32_e32 v59, v29, v28
	v_and_b32_e32 v28, 0xffff0000, v34
	v_and_b32_e32 v26, 0xffff0000, v26
	v_add_f32_e32 v19, v48, v19
	v_lshlrev_b32_e32 v49, 16, v36
	v_and_b32_e32 v48, 0xffff0000, v36
	v_add_f32_e32 v56, v24, v25
	v_lshlrev_b32_e32 v25, 16, v37
	v_and_b32_e32 v24, 0xffff0000, v37
	v_add_f32_e32 v60, v28, v26
	v_lshlrev_b32_e32 v37, 16, v30
	v_and_b32_e32 v36, 0xffff0000, v30
	v_lshlrev_b32_e32 v26, 16, v27
	v_lshlrev_b32_e32 v30, 16, v35
	v_add_f32_e32 v63, v30, v26
	v_and_b32_e32 v26, 0xffff0000, v35
	v_lshlrev_b32_e32 v35, 16, v31
	v_and_b32_e32 v34, 0xffff0000, v31
	v_pk_add_f32 v[30:31], v[50:51], v[48:49]
	v_mul_f32_e32 v48, v19, v19
	v_fmac_f32_e32 v48, v52, v52
	v_fmac_f32_e32 v48, v55, v55
	v_fmac_f32_e32 v48, v56, v56
	v_fmac_f32_e32 v48, v59, v59
	v_and_b32_e32 v27, 0xffff0000, v27
	v_fmac_f32_e32 v48, v60, v60
	v_add_f32_e32 v64, v26, v27
	v_fmac_f32_e32 v48, v63, v63
	v_lshlrev_b32_e32 v29, 16, v38
	v_and_b32_e32 v28, 0xffff0000, v38
	v_lshlrev_b32_e32 v27, 16, v39
	v_and_b32_e32 v26, 0xffff0000, v39
	v_pk_mul_f32 v[38:39], v[30:31], v[30:31]
	v_fmac_f32_e32 v48, v64, v64
	v_pk_add_f32 v[32:33], v[32:33], v[24:25]
	v_add_f32_e32 v39, v39, v48
	v_pk_mul_f32 v[24:25], v[32:33], v[32:33]
	v_add_f32_e32 v38, v38, v39
	v_pk_add_f32 v[36:37], v[36:37], v[28:29]
	v_add_f32_e32 v25, v25, v38
	v_pk_mul_f32 v[28:29], v[36:37], v[36:37]
	v_add_f32_e32 v24, v24, v25
	v_pk_add_f32 v[34:35], v[34:35], v[26:27]
	v_add_f32_e32 v24, v29, v24
	v_pk_mul_f32 v[26:27], v[34:35], v[34:35]
	v_add_f32_e32 v24, v28, v24
	v_add_f32_e32 v24, v27, v24
	v_add_f32_e32 v24, v26, v24
	ds_bpermute_b32 v25, v0, v24
	v_lshlrev_b32_e32 v53, 16, v44
	v_and_b32_e32 v44, 0xffff0000, v44
	v_lshlrev_b32_e32 v54, 16, v40
	v_and_b32_e32 v40, 0xffff0000, v40
	s_waitcnt lgkmcnt(0)
	v_add_f32_e32 v24, v24, v25
	ds_bpermute_b32 v25, v22, v24
	v_lshlrev_b32_e32 v57, 16, v45
	v_and_b32_e32 v45, 0xffff0000, v45
	v_lshlrev_b32_e32 v58, 16, v41
	v_and_b32_e32 v41, 0xffff0000, v41
	s_waitcnt lgkmcnt(0)
	v_add_f32_e32 v24, v24, v25
	ds_bpermute_b32 v25, v23, v24
	v_lshlrev_b32_e32 v61, 16, v46
	v_and_b32_e32 v46, 0xffff0000, v46
	v_lshlrev_b32_e32 v62, 16, v42
	v_and_b32_e32 v42, 0xffff0000, v42
	s_waitcnt lgkmcnt(0)
	v_add_f32_e32 v24, v24, v25
	v_fmamk_f32 v24, v24, 0x3c000000, v186
	v_cmp_gt_f32_e32 vcc, s7, v24
	v_mul_f32_e32 v25, 0x4b800000, v24
	v_lshlrev_b32_e32 v65, 16, v47
	v_cndmask_b32_e32 v24, v24, v25, vcc
	v_rsq_f32_e32 v24, v24
	v_and_b32_e32 v47, 0xffff0000, v47
	v_lshlrev_b32_e32 v66, 16, v43
	v_and_b32_e32 v43, 0xffff0000, v43
	v_mul_f32_e32 v25, 0x45800000, v24
	v_cndmask_b32_e32 v38, v24, v25, vcc
	v_mul_f32_e32 v19, v19, v38
	v_mul_f32_e32 v24, v52, v38
	v_mul_f32_e32 v19, v2, v19
	v_mul_f32_e32 v24, v3, v24
	v_mul_f32_e32 v19, v19, v53
	v_mul_f32_e32 v24, v24, v44
	v_cvt_pk_bf16_f32 v24, v19, v24
	v_mul_f32_e32 v19, v31, v38
	v_mul_f32_e32 v25, v30, v38
	v_mul_f32_e32 v19, v10, v19
	v_mul_f32_e32 v25, v11, v25
	v_mul_f32_e32 v19, v19, v54
	v_mul_f32_e32 v25, v25, v40
	v_cvt_pk_bf16_f32 v28, v19, v25
	v_mul_f32_e32 v19, v55, v38
	v_mul_f32_e32 v25, v56, v38
	v_mul_f32_e32 v19, v4, v19
	v_mul_f32_e32 v25, v5, v25
	v_mul_f32_e32 v19, v19, v57
	v_mul_f32_e32 v25, v25, v45
	v_cvt_pk_bf16_f32 v25, v19, v25
	v_mul_f32_e32 v19, v33, v38
	v_mul_f32_e32 v26, v32, v38
	v_mul_f32_e32 v19, v12, v19
	v_mul_f32_e32 v26, v13, v26
	v_mul_f32_e32 v19, v19, v58
	v_mul_f32_e32 v26, v26, v41
	v_cvt_pk_bf16_f32 v29, v19, v26
	v_mul_f32_e32 v19, v59, v38
	v_mul_f32_e32 v26, v60, v38
	v_mul_f32_e32 v19, v6, v19
	v_mul_f32_e32 v26, v7, v26
	v_mul_f32_e32 v19, v19, v61
	v_mul_f32_e32 v26, v26, v46
	v_cvt_pk_bf16_f32 v26, v19, v26
	v_mul_f32_e32 v19, v37, v38
	v_mul_f32_e32 v27, v36, v38
	v_mul_f32_e32 v19, v14, v19
	v_mul_f32_e32 v27, v15, v27
	v_mul_f32_e32 v19, v19, v62
	v_mul_f32_e32 v27, v27, v42
	v_cvt_pk_bf16_f32 v30, v19, v27
	v_mul_f32_e32 v19, v63, v38
	v_mul_f32_e32 v27, v64, v38
	v_mul_f32_e32 v19, v8, v19
	v_mul_f32_e32 v27, v9, v27
	v_add_co_u32_e32 v32, vcc, 0xec000000, v20
	v_mul_f32_e32 v19, v19, v65
	v_mul_f32_e32 v27, v27, v47
	v_mul_f32_e32 v31, v34, v38
	v_addc_co_u32_e32 v33, vcc, -1, v21, vcc
	v_cvt_pk_bf16_f32 v27, v19, v27
	v_mul_f32_e32 v19, v35, v38
	v_mul_f32_e32 v31, v17, v31
	v_cmp_lt_i32_e32 vcc, s14, v18
	v_mul_f32_e32 v19, v16, v19
	v_mul_f32_e32 v31, v31, v43
	v_lshl_add_u64 v[20:21], v[20:21], 0, s[20:21]
	s_or_b64 s[10:11], vcc, s[10:11]
	v_mul_f32_e32 v19, v19, v66
	v_cvt_pk_bf16_f32 v31, v19, v31
	global_store_dwordx4 v[32:33], v[24:27], off offset:-16
	global_store_dwordx4 v[32:33], v[28:31], off
	s_andn2_b64 exec, exec, s[10:11]
	s_cbranch_execnz .LBB0_1061
.LBB0_1062:
	s_or_b64 exec, exec, s[8:9]
	s_waitcnt vmcnt(0)
.LBB0_1063:
	v_readlane_b32 s28, v255, 1
	v_readlane_b32 s30, v255, 3
	v_readlane_b32 s29, v255, 2
	v_readlane_b32 s31, v255, 4
	s_branch .LBB0_1486
